# fused P9 epilogue: residual phase and output phase visit row groups in a per-wave rotated order
# speedup vs baseline: 1.0080x; 1.0080x over previous
; #define PG8_LAS __attribute__((address_space(3)))
; __device__ __forceinline__ u32x4 pack8(const f32x4 a, const f32x4 b) { u32x4 w; w.x = cvt_pk_bf16(a[0], a[1]); w.y = cvt_pk_bf16(a[2], a[3]); w.z = cvt_pk_bf16(b[0], b[1]); w.w = cvt_pk_bf16(b[2], b[3]); return w; }
;     __device__ __forceinline__ void operator()(const f32x4 (&acc)[2][2][4][2], const Unit& u, int wr, int wc, int fr, int fq) const {
;     ...
;         const int b = u.pm >> 5, col0 = u.pn * BM + wc * 64 + fq * 8;
;         PG8_LAS unsigned char* st = stg + (wr * 4 + wc) * 1024;
;         f32x4 gv[2][2], cs[2][2];
; #pragma unroll
;         for (int bj = 0; bj < 2; ++bj)
; #pragma unroll
;             for (int n = 0; n < 2; ++n) { const int c = col0 + bj * 32 + 4 * n; gv[bj][n] = *(const f32x4*)(gate + (size_t)b * NMODC + c) * (HALFG ? 0.5f : 1.0f);
;                 cs[bj][n] = (f32x4){0.f, 0.f, 0.f, 0.f}; if (XS) cs[bj][n] = *(const f32x4*)(gcol + c) * (*(const f32x4*)(scm + (size_t)b * NMODC + c) + 1.0f); }
;         u32x4 c16[2], n16[2]; f32x4 c32[2][2], n32[2][2];
;     ...
;         RES_LOAD(c16, c32, 0);
; #pragma unroll
;         for (int r = 0; r < 8; ++r) { const int ai = r >> 2, m = r & 3; const int row = EPI_ROW; float sq = 0.f;
;             if (r < 7) RES_LOAD(n16, n32, r + 1);
;             u32x4 pn_[2], ps_[2];
; #pragma unroll
;             for (int bj = 0; bj < 2; ++bj) {
;                 f32x4 o0, o1;
;                 if (XOLD16) unpack8(c16[bj], o0, o1); else { o0 = c32[bj][0]; o1 = c32[bj][1]; }
;                 const f32x4 v0 = o0 + gv[bj][0] * acc[ai][bj][m][0], v1 = o1 + gv[bj][1] * acc[ai][bj][m][1];
;                 pn_[bj] = pack8(v0, v1);
;                 sq += ((v0[0] * v0[0] + v0[1] * v0[1]) + (v0[2] * v0[2] + v0[3] * v0[3])) + ((v1[0] * v1[0] + v1[1] * v1[1]) + (v1[2] * v1[2] + v1[3] * v1[3]));
;                 if (XS) ps_[bj] = pack8(v0 * cs[bj][0], v1 * cs[bj][1]); }
.LBB0_1072:
	s_mov_b32 s98, s34
	v_readlane_b32 s34, v254, 1
	v_readlane_b32 s35, v254, 2
	s_lshl_b32 s0, s10, 8
	s_or_b32 s0, s0, s57
	s_lshl_b32 s1, s98, 8
	s_add_i32 s1, s1, s54
	s_load_dwordx2 s[100:101], s[34:35], 0x88
	s_ashr_i32 s4, s98, 5
	s_mul_i32 s4, s4, 0x9000
	s_add_u32 s6, s51, s4
	s_addc_u32 s7, s52, 0
	s_lshl_b32 s4, s0, 2
	s_add_u32 s6, s6, s4
	s_addc_u32 s7, s7, 0
	v_lshlrev_b32_e32 v188, 5, v190
	global_load_dwordx4 v[168:171], v188, s[6:7]
	global_load_dwordx4 v[164:167], v188, s[6:7] offset:16
	global_load_dwordx4 v[160:163], v188, s[6:7] offset:128
	global_load_dwordx4 v[156:159], v188, s[6:7] offset:144
	s_lshl_b32 s4, s1, 11
	s_lshl_b32 s5, s0, 1
	s_add_u32 s4, s4, s5
	s_add_u32 s36, s78, 0x18000000
	s_addc_u32 s37, s79, 0
	s_add_u32 s36, s36, s4
	s_addc_u32 s37, s37, 0
	v_lshlrev_b32_e32 v189, 11, v1
	v_lshl_add_u32 v189, v190, 4, v189
	global_load_dwordx4 v[196:199], v189, s[36:37]
	global_load_dwordx4 v[200:203], v189, s[36:37] offset:64
	s_add_u32 s36, s36, 0x8000
	s_addc_u32 s37, s37, 0
	global_load_dwordx4 v[204:207], v189, s[36:37]
	global_load_dwordx4 v[208:211], v189, s[36:37] offset:64
	s_add_u32 s36, s36, 0x8000
	s_addc_u32 s37, s37, 0
	global_load_dwordx4 v[212:215], v189, s[36:37]
	global_load_dwordx4 v[216:219], v189, s[36:37] offset:64
	s_add_u32 s36, s36, 0x8000
	s_addc_u32 s37, s37, 0
	global_load_dwordx4 v[220:223], v189, s[36:37]
	global_load_dwordx4 v[224:227], v189, s[36:37] offset:64
	s_add_u32 s36, s36, 0x28000
	s_addc_u32 s37, s37, 0
	global_load_dwordx4 v[228:231], v189, s[36:37]
	global_load_dwordx4 v[232:235], v189, s[36:37] offset:64
	s_add_u32 s36, s36, 0x8000
	s_addc_u32 s37, s37, 0
	global_load_dwordx4 v[236:239], v189, s[36:37]
	global_load_dwordx4 v[240:243], v189, s[36:37] offset:64
	s_add_u32 s36, s36, 0x8000
	s_addc_u32 s37, s37, 0
	global_load_dwordx4 v[244:247], v189, s[36:37]
	global_load_dwordx4 v[248:251], v189, s[36:37] offset:64
	s_add_u32 s36, s36, 0x8000
	s_addc_u32 s37, s37, 0
	global_load_dwordx4 v[130:133], v189, s[36:37]
	global_load_dwordx4 v[134:137], v189, s[36:37] offset:64
	v_xor_b32_e32 v255, 16, v195
	v_xor_b32_e32 v252, 32, v195
	v_lshlrev_b32_e32 v255, 2, v255
	v_lshlrev_b32_e32 v252, 2, v252
	v_lshlrev_b32_e32 v146, 6, v1
	s_waitcnt vmcnt(16)
	v_pk_mul_f32 v[156:157], v[156:157], 0.5 op_sel_hi:[1,0]
	v_pk_mul_f32 v[158:159], v[158:159], 0.5 op_sel_hi:[1,0]
	v_pk_mul_f32 v[160:161], v[160:161], 0.5 op_sel_hi:[1,0]
	v_pk_mul_f32 v[162:163], v[162:163], 0.5 op_sel_hi:[1,0]
	v_pk_mul_f32 v[164:165], v[164:165], 0.5 op_sel_hi:[1,0]
	v_pk_mul_f32 v[166:167], v[166:167], 0.5 op_sel_hi:[1,0]
	v_pk_mul_f32 v[168:169], v[168:169], 0.5 op_sel_hi:[1,0]
	v_pk_mul_f32 v[170:171], v[170:171], 0.5 op_sel_hi:[1,0]
	s_lshr_b32 s4, s54, 4
	s_add_u32 s4, s4, s53
	s_mov_b32 s5, 8
	s_cmp_eq_u32 s4, 1
	s_cbranch_scc1 .Lf9a_rg1
	s_cmp_eq_u32 s4, 2
	s_cbranch_scc1 .Lf9a_rg2
	s_cmp_eq_u32 s4, 3
	s_cbranch_scc1 .Lf9a_rg3
	s_cmp_eq_u32 s4, 4
	s_cbranch_scc1 .Lf9a_rg4
	s_cmp_eq_u32 s4, 5
	s_cbranch_scc1 .Lf9a_rg5
	s_cmp_eq_u32 s4, 6
	s_cbranch_scc1 .Lf9a_rg6
	s_cmp_eq_u32 s4, 7
	s_cbranch_scc1 .Lf9a_rg7
.Lf9a_rg0:
	s_waitcnt vmcnt(14)
	v_lshlrev_b32_e32 v184, 16, v196
	v_and_b32_e32 v185, 0xffff0000, v196
	v_lshlrev_b32_e32 v186, 16, v197
	v_and_b32_e32 v187, 0xffff0000, v197
	v_lshlrev_b32_e32 v180, 16, v198
	v_and_b32_e32 v181, 0xffff0000, v198
	v_lshlrev_b32_e32 v182, 16, v199
	v_and_b32_e32 v183, 0xffff0000, v199
	v_lshlrev_b32_e32 v176, 16, v200
	v_and_b32_e32 v177, 0xffff0000, v200
	v_lshlrev_b32_e32 v178, 16, v201
	v_and_b32_e32 v179, 0xffff0000, v201
	v_lshlrev_b32_e32 v172, 16, v202
	v_and_b32_e32 v173, 0xffff0000, v202
	v_lshlrev_b32_e32 v174, 16, v203
	v_and_b32_e32 v175, 0xffff0000, v203
	v_pk_fma_f32 v[114:115], v[114:115], v[156:157], v[172:173]
	v_pk_fma_f32 v[116:117], v[116:117], v[158:159], v[174:175]
	v_pk_fma_f32 v[118:119], v[118:119], v[160:161], v[176:177]
	v_pk_fma_f32 v[120:121], v[120:121], v[162:163], v[178:179]
	v_pk_fma_f32 v[122:123], v[122:123], v[164:165], v[180:181]
	v_pk_fma_f32 v[124:125], v[124:125], v[166:167], v[182:183]
	v_pk_fma_f32 v[126:127], v[126:127], v[168:169], v[184:185]
	v_pk_fma_f32 v[128:129], v[128:129], v[170:171], v[186:187]
	v_mul_f32_e32 v172, v127, v127
	v_mul_f32_e32 v173, v129, v129
	v_fmac_f32_e32 v172, v126, v126
	v_fmac_f32_e32 v173, v128, v128
	v_add_f32_e32 v172, v172, v173
	v_mul_f32_e32 v173, v123, v123
	v_mul_f32_e32 v174, v125, v125
	v_fmac_f32_e32 v173, v122, v122
	v_fmac_f32_e32 v174, v124, v124
	v_add_f32_e32 v173, v173, v174
	v_add_f32_e32 v172, v172, v173
	v_mul_f32_e32 v173, v119, v119
	v_mul_f32_e32 v174, v121, v121
	v_fmac_f32_e32 v173, v118, v118
	v_fmac_f32_e32 v174, v120, v120
	v_add_f32_e32 v173, v173, v174
	v_mul_f32_e32 v174, v115, v115
	v_mul_f32_e32 v175, v117, v117
	v_fmac_f32_e32 v174, v114, v114
	v_fmac_f32_e32 v175, v116, v116
	v_add_f32_e32 v174, v174, v175
	v_add_f32_e32 v173, v173, v174
	v_add_f32_e32 v196, v172, v173
	s_add_i32 s5, s5, -1
	s_cmp_eq_u32 s5, 0
	s_cbranch_scc1 .Lf9a_done
; __device__ __forceinline__ u32x4 pack8(const f32x4 a, const f32x4 b) { u32x4 w; w.x = cvt_pk_bf16(a[0], a[1]); w.y = cvt_pk_bf16(a[2], a[3]); w.z = cvt_pk_bf16(b[0], b[1]); w.w = cvt_pk_bf16(b[2], b[3]); return w; }
;     __device__ __forceinline__ void operator()(const f32x4 (&acc)[2][2][4][2], const Unit& u, int wr, int wc, int fr, int fq) const {
;     ...
;         for (int r = 0; r < 8; ++r) { const int ai = r >> 2, m = r & 3; const int row = EPI_ROW; float sq = 0.f;
;             if (r < 7) RES_LOAD(n16, n32, r + 1);
;             u32x4 pn_[2], ps_[2];
; #pragma unroll
;             for (int bj = 0; bj < 2; ++bj) {
;                 f32x4 o0, o1;
;                 if (XOLD16) unpack8(c16[bj], o0, o1); else { o0 = c32[bj][0]; o1 = c32[bj][1]; }
;                 const f32x4 v0 = o0 + gv[bj][0] * acc[ai][bj][m][0], v1 = o1 + gv[bj][1] * acc[ai][bj][m][1];
;                 pn_[bj] = pack8(v0, v1);
;                 sq += ((v0[0] * v0[0] + v0[1] * v0[1]) + (v0[2] * v0[2] + v0[3] * v0[3])) + ((v1[0] * v1[0] + v1[1] * v1[1]) + (v1[2] * v1[2] + v1[3] * v1[3]));
;                 if (XS) ps_[bj] = pack8(v0 * cs[bj][0], v1 * cs[bj][1]); }
.Lf9a_rg1:
	s_waitcnt vmcnt(12)
	v_lshlrev_b32_e32 v184, 16, v204
	v_and_b32_e32 v185, 0xffff0000, v204
	v_lshlrev_b32_e32 v186, 16, v205
	v_and_b32_e32 v187, 0xffff0000, v205
	v_lshlrev_b32_e32 v180, 16, v206
	v_and_b32_e32 v181, 0xffff0000, v206
	v_lshlrev_b32_e32 v182, 16, v207
	v_and_b32_e32 v183, 0xffff0000, v207
	v_lshlrev_b32_e32 v176, 16, v208
	v_and_b32_e32 v177, 0xffff0000, v208
	v_lshlrev_b32_e32 v178, 16, v209
	v_and_b32_e32 v179, 0xffff0000, v209
	v_lshlrev_b32_e32 v172, 16, v210
	v_and_b32_e32 v173, 0xffff0000, v210
	v_lshlrev_b32_e32 v174, 16, v211
	v_and_b32_e32 v175, 0xffff0000, v211
	v_pk_fma_f32 v[98:99], v[98:99], v[156:157], v[172:173]
	v_pk_fma_f32 v[100:101], v[100:101], v[158:159], v[174:175]
	v_pk_fma_f32 v[102:103], v[102:103], v[160:161], v[176:177]
	v_pk_fma_f32 v[104:105], v[104:105], v[162:163], v[178:179]
	v_pk_fma_f32 v[106:107], v[106:107], v[164:165], v[180:181]
	v_pk_fma_f32 v[108:109], v[108:109], v[166:167], v[182:183]
	v_pk_fma_f32 v[110:111], v[110:111], v[168:169], v[184:185]
	v_pk_fma_f32 v[112:113], v[112:113], v[170:171], v[186:187]
	v_mul_f32_e32 v172, v111, v111
	v_mul_f32_e32 v173, v113, v113
	v_fmac_f32_e32 v172, v110, v110
	v_fmac_f32_e32 v173, v112, v112
	v_add_f32_e32 v172, v172, v173
	v_mul_f32_e32 v173, v107, v107
	v_mul_f32_e32 v174, v109, v109
	v_fmac_f32_e32 v173, v106, v106
	v_fmac_f32_e32 v174, v108, v108
	v_add_f32_e32 v173, v173, v174
	v_add_f32_e32 v172, v172, v173
	v_mul_f32_e32 v173, v103, v103
	v_mul_f32_e32 v174, v105, v105
	v_fmac_f32_e32 v173, v102, v102
	v_fmac_f32_e32 v174, v104, v104
	v_add_f32_e32 v173, v173, v174
	v_mul_f32_e32 v174, v99, v99
	v_mul_f32_e32 v175, v101, v101
	v_fmac_f32_e32 v174, v98, v98
	v_fmac_f32_e32 v175, v100, v100
	v_add_f32_e32 v174, v174, v175
	v_add_f32_e32 v173, v173, v174
	v_add_f32_e32 v204, v172, v173
	s_add_i32 s5, s5, -1
	s_cmp_eq_u32 s5, 0
	s_cbranch_scc1 .Lf9a_done
.Lf9a_rg2:
	s_waitcnt vmcnt(10)
	v_lshlrev_b32_e32 v184, 16, v212
	v_and_b32_e32 v185, 0xffff0000, v212
	v_lshlrev_b32_e32 v186, 16, v213
	v_and_b32_e32 v187, 0xffff0000, v213
	v_lshlrev_b32_e32 v180, 16, v214
	v_and_b32_e32 v181, 0xffff0000, v214
	v_lshlrev_b32_e32 v182, 16, v215
	v_and_b32_e32 v183, 0xffff0000, v215
	v_lshlrev_b32_e32 v176, 16, v216
	v_and_b32_e32 v177, 0xffff0000, v216
	v_lshlrev_b32_e32 v178, 16, v217
	v_and_b32_e32 v179, 0xffff0000, v217
	v_lshlrev_b32_e32 v172, 16, v218
	v_and_b32_e32 v173, 0xffff0000, v218
	v_lshlrev_b32_e32 v174, 16, v219
	v_and_b32_e32 v175, 0xffff0000, v219
	v_pk_fma_f32 v[82:83], v[82:83], v[156:157], v[172:173]
	v_pk_fma_f32 v[84:85], v[84:85], v[158:159], v[174:175]
	v_pk_fma_f32 v[86:87], v[86:87], v[160:161], v[176:177]
	v_pk_fma_f32 v[88:89], v[88:89], v[162:163], v[178:179]
	v_pk_fma_f32 v[90:91], v[90:91], v[164:165], v[180:181]
	v_pk_fma_f32 v[92:93], v[92:93], v[166:167], v[182:183]
	v_pk_fma_f32 v[94:95], v[94:95], v[168:169], v[184:185]
	v_pk_fma_f32 v[96:97], v[96:97], v[170:171], v[186:187]
	v_mul_f32_e32 v172, v95, v95
	v_mul_f32_e32 v173, v97, v97
	v_fmac_f32_e32 v172, v94, v94
	v_fmac_f32_e32 v173, v96, v96
	v_add_f32_e32 v172, v172, v173
	v_mul_f32_e32 v173, v91, v91
	v_mul_f32_e32 v174, v93, v93
	v_fmac_f32_e32 v173, v90, v90
	v_fmac_f32_e32 v174, v92, v92
	v_add_f32_e32 v173, v173, v174
	v_add_f32_e32 v172, v172, v173
	v_mul_f32_e32 v173, v87, v87
	v_mul_f32_e32 v174, v89, v89
	v_fmac_f32_e32 v173, v86, v86
	v_fmac_f32_e32 v174, v88, v88
	v_add_f32_e32 v173, v173, v174
	v_mul_f32_e32 v174, v83, v83
	v_mul_f32_e32 v175, v85, v85
	v_fmac_f32_e32 v174, v82, v82
	v_fmac_f32_e32 v175, v84, v84
	v_add_f32_e32 v174, v174, v175
	v_add_f32_e32 v173, v173, v174
	v_add_f32_e32 v212, v172, v173
	s_add_i32 s5, s5, -1
	s_cmp_eq_u32 s5, 0
	s_cbranch_scc1 .Lf9a_done
.Lf9a_rg3:
	s_waitcnt vmcnt(8)
	v_lshlrev_b32_e32 v184, 16, v220
	v_and_b32_e32 v185, 0xffff0000, v220
	v_lshlrev_b32_e32 v186, 16, v221
	v_and_b32_e32 v187, 0xffff0000, v221
	v_lshlrev_b32_e32 v180, 16, v222
	v_and_b32_e32 v181, 0xffff0000, v222
	v_lshlrev_b32_e32 v182, 16, v223
	v_and_b32_e32 v183, 0xffff0000, v223
	v_lshlrev_b32_e32 v176, 16, v224
	v_and_b32_e32 v177, 0xffff0000, v224
	v_lshlrev_b32_e32 v178, 16, v225
	v_and_b32_e32 v179, 0xffff0000, v225
	v_lshlrev_b32_e32 v172, 16, v226
	v_and_b32_e32 v173, 0xffff0000, v226
	v_lshlrev_b32_e32 v174, 16, v227
	v_and_b32_e32 v175, 0xffff0000, v227
	v_pk_fma_f32 v[66:67], v[66:67], v[156:157], v[172:173]
	v_pk_fma_f32 v[68:69], v[68:69], v[158:159], v[174:175]
	v_pk_fma_f32 v[70:71], v[70:71], v[160:161], v[176:177]
	v_pk_fma_f32 v[72:73], v[72:73], v[162:163], v[178:179]
	v_pk_fma_f32 v[74:75], v[74:75], v[164:165], v[180:181]
	v_pk_fma_f32 v[76:77], v[76:77], v[166:167], v[182:183]
	v_pk_fma_f32 v[78:79], v[78:79], v[168:169], v[184:185]
	v_pk_fma_f32 v[80:81], v[80:81], v[170:171], v[186:187]
	v_mul_f32_e32 v172, v79, v79
	v_mul_f32_e32 v173, v81, v81
	v_fmac_f32_e32 v172, v78, v78
	v_fmac_f32_e32 v173, v80, v80
	v_add_f32_e32 v172, v172, v173
	v_mul_f32_e32 v173, v75, v75
	v_mul_f32_e32 v174, v77, v77
	v_fmac_f32_e32 v173, v74, v74
	v_fmac_f32_e32 v174, v76, v76
	v_add_f32_e32 v173, v173, v174
	v_add_f32_e32 v172, v172, v173
	v_mul_f32_e32 v173, v71, v71
	v_mul_f32_e32 v174, v73, v73
	v_fmac_f32_e32 v173, v70, v70
	v_fmac_f32_e32 v174, v72, v72
	v_add_f32_e32 v173, v173, v174
	v_mul_f32_e32 v174, v67, v67
	v_mul_f32_e32 v175, v69, v69
	v_fmac_f32_e32 v174, v66, v66
	v_fmac_f32_e32 v175, v68, v68
	v_add_f32_e32 v174, v174, v175
	v_add_f32_e32 v173, v173, v174
	v_add_f32_e32 v220, v172, v173
	s_add_i32 s5, s5, -1
	s_cmp_eq_u32 s5, 0
	s_cbranch_scc1 .Lf9a_done
; __device__ __forceinline__ u32x4 pack8(const f32x4 a, const f32x4 b) { u32x4 w; w.x = cvt_pk_bf16(a[0], a[1]); w.y = cvt_pk_bf16(a[2], a[3]); w.z = cvt_pk_bf16(b[0], b[1]); w.w = cvt_pk_bf16(b[2], b[3]); return w; }
;     __device__ __forceinline__ void operator()(const f32x4 (&acc)[2][2][4][2], const Unit& u, int wr, int wc, int fr, int fq) const {
;     ...
;         for (int r = 0; r < 8; ++r) { const int ai = r >> 2, m = r & 3; const int row = EPI_ROW; float sq = 0.f;
;             if (r < 7) RES_LOAD(n16, n32, r + 1);
;             u32x4 pn_[2], ps_[2];
; #pragma unroll
;             for (int bj = 0; bj < 2; ++bj) {
;                 f32x4 o0, o1;
;                 if (XOLD16) unpack8(c16[bj], o0, o1); else { o0 = c32[bj][0]; o1 = c32[bj][1]; }
;                 const f32x4 v0 = o0 + gv[bj][0] * acc[ai][bj][m][0], v1 = o1 + gv[bj][1] * acc[ai][bj][m][1];
;                 pn_[bj] = pack8(v0, v1);
;                 sq += ((v0[0] * v0[0] + v0[1] * v0[1]) + (v0[2] * v0[2] + v0[3] * v0[3])) + ((v1[0] * v1[0] + v1[1] * v1[1]) + (v1[2] * v1[2] + v1[3] * v1[3]));
;                 if (XS) ps_[bj] = pack8(v0 * cs[bj][0], v1 * cs[bj][1]); }
.Lf9a_rg4:
	s_waitcnt vmcnt(6)
	v_lshlrev_b32_e32 v184, 16, v228
	v_and_b32_e32 v185, 0xffff0000, v228
	v_lshlrev_b32_e32 v186, 16, v229
	v_and_b32_e32 v187, 0xffff0000, v229
	v_lshlrev_b32_e32 v180, 16, v230
	v_and_b32_e32 v181, 0xffff0000, v230
	v_lshlrev_b32_e32 v182, 16, v231
	v_and_b32_e32 v183, 0xffff0000, v231
	v_lshlrev_b32_e32 v176, 16, v232
	v_and_b32_e32 v177, 0xffff0000, v232
	v_lshlrev_b32_e32 v178, 16, v233
	v_and_b32_e32 v179, 0xffff0000, v233
	v_lshlrev_b32_e32 v172, 16, v234
	v_and_b32_e32 v173, 0xffff0000, v234
	v_lshlrev_b32_e32 v174, 16, v235
	v_and_b32_e32 v175, 0xffff0000, v235
	v_pk_fma_f32 v[50:51], v[50:51], v[156:157], v[172:173]
	v_pk_fma_f32 v[52:53], v[52:53], v[158:159], v[174:175]
	v_pk_fma_f32 v[54:55], v[54:55], v[160:161], v[176:177]
	v_pk_fma_f32 v[56:57], v[56:57], v[162:163], v[178:179]
	v_pk_fma_f32 v[58:59], v[58:59], v[164:165], v[180:181]
	v_pk_fma_f32 v[60:61], v[60:61], v[166:167], v[182:183]
	v_pk_fma_f32 v[62:63], v[62:63], v[168:169], v[184:185]
	v_pk_fma_f32 v[64:65], v[64:65], v[170:171], v[186:187]
	v_mul_f32_e32 v172, v63, v63
	v_mul_f32_e32 v173, v65, v65
	v_fmac_f32_e32 v172, v62, v62
	v_fmac_f32_e32 v173, v64, v64
	v_add_f32_e32 v172, v172, v173
	v_mul_f32_e32 v173, v59, v59
	v_mul_f32_e32 v174, v61, v61
	v_fmac_f32_e32 v173, v58, v58
	v_fmac_f32_e32 v174, v60, v60
	v_add_f32_e32 v173, v173, v174
	v_add_f32_e32 v172, v172, v173
	v_mul_f32_e32 v173, v55, v55
	v_mul_f32_e32 v174, v57, v57
	v_fmac_f32_e32 v173, v54, v54
	v_fmac_f32_e32 v174, v56, v56
	v_add_f32_e32 v173, v173, v174
	v_mul_f32_e32 v174, v51, v51
	v_mul_f32_e32 v175, v53, v53
	v_fmac_f32_e32 v174, v50, v50
	v_fmac_f32_e32 v175, v52, v52
	v_add_f32_e32 v174, v174, v175
	v_add_f32_e32 v173, v173, v174
	v_add_f32_e32 v228, v172, v173
	s_add_i32 s5, s5, -1
	s_cmp_eq_u32 s5, 0
	s_cbranch_scc1 .Lf9a_done
.Lf9a_rg5:
	s_waitcnt vmcnt(4)
	v_lshlrev_b32_e32 v184, 16, v236
	v_and_b32_e32 v185, 0xffff0000, v236
	v_lshlrev_b32_e32 v186, 16, v237
	v_and_b32_e32 v187, 0xffff0000, v237
	v_lshlrev_b32_e32 v180, 16, v238
	v_and_b32_e32 v181, 0xffff0000, v238
	v_lshlrev_b32_e32 v182, 16, v239
	v_and_b32_e32 v183, 0xffff0000, v239
	v_lshlrev_b32_e32 v176, 16, v240
	v_and_b32_e32 v177, 0xffff0000, v240
	v_lshlrev_b32_e32 v178, 16, v241
	v_and_b32_e32 v179, 0xffff0000, v241
	v_lshlrev_b32_e32 v172, 16, v242
	v_and_b32_e32 v173, 0xffff0000, v242
	v_lshlrev_b32_e32 v174, 16, v243
	v_and_b32_e32 v175, 0xffff0000, v243
	v_pk_fma_f32 v[34:35], v[34:35], v[156:157], v[172:173]
	v_pk_fma_f32 v[36:37], v[36:37], v[158:159], v[174:175]
	v_pk_fma_f32 v[38:39], v[38:39], v[160:161], v[176:177]
	v_pk_fma_f32 v[40:41], v[40:41], v[162:163], v[178:179]
	v_pk_fma_f32 v[42:43], v[42:43], v[164:165], v[180:181]
	v_pk_fma_f32 v[44:45], v[44:45], v[166:167], v[182:183]
	v_pk_fma_f32 v[46:47], v[46:47], v[168:169], v[184:185]
	v_pk_fma_f32 v[48:49], v[48:49], v[170:171], v[186:187]
	v_mul_f32_e32 v172, v47, v47
	v_mul_f32_e32 v173, v49, v49
	v_fmac_f32_e32 v172, v46, v46
	v_fmac_f32_e32 v173, v48, v48
	v_add_f32_e32 v172, v172, v173
	v_mul_f32_e32 v173, v43, v43
	v_mul_f32_e32 v174, v45, v45
	v_fmac_f32_e32 v173, v42, v42
	v_fmac_f32_e32 v174, v44, v44
	v_add_f32_e32 v173, v173, v174
	v_add_f32_e32 v172, v172, v173
	v_mul_f32_e32 v173, v39, v39
	v_mul_f32_e32 v174, v41, v41
	v_fmac_f32_e32 v173, v38, v38
	v_fmac_f32_e32 v174, v40, v40
	v_add_f32_e32 v173, v173, v174
	v_mul_f32_e32 v174, v35, v35
	v_mul_f32_e32 v175, v37, v37
	v_fmac_f32_e32 v174, v34, v34
	v_fmac_f32_e32 v175, v36, v36
	v_add_f32_e32 v174, v174, v175
	v_add_f32_e32 v173, v173, v174
	v_add_f32_e32 v236, v172, v173
	s_add_i32 s5, s5, -1
	s_cmp_eq_u32 s5, 0
	s_cbranch_scc1 .Lf9a_done
.Lf9a_rg6:
	s_waitcnt vmcnt(2)
	v_lshlrev_b32_e32 v184, 16, v244
	v_and_b32_e32 v185, 0xffff0000, v244
	v_lshlrev_b32_e32 v186, 16, v245
	v_and_b32_e32 v187, 0xffff0000, v245
	v_lshlrev_b32_e32 v180, 16, v246
	v_and_b32_e32 v181, 0xffff0000, v246
	v_lshlrev_b32_e32 v182, 16, v247
	v_and_b32_e32 v183, 0xffff0000, v247
	v_lshlrev_b32_e32 v176, 16, v248
	v_and_b32_e32 v177, 0xffff0000, v248
	v_lshlrev_b32_e32 v178, 16, v249
	v_and_b32_e32 v179, 0xffff0000, v249
	v_lshlrev_b32_e32 v172, 16, v250
	v_and_b32_e32 v173, 0xffff0000, v250
	v_lshlrev_b32_e32 v174, 16, v251
	v_and_b32_e32 v175, 0xffff0000, v251
	v_pk_fma_f32 v[18:19], v[18:19], v[156:157], v[172:173]
	v_pk_fma_f32 v[20:21], v[20:21], v[158:159], v[174:175]
	v_pk_fma_f32 v[22:23], v[22:23], v[160:161], v[176:177]
	v_pk_fma_f32 v[24:25], v[24:25], v[162:163], v[178:179]
	v_pk_fma_f32 v[26:27], v[26:27], v[164:165], v[180:181]
	v_pk_fma_f32 v[28:29], v[28:29], v[166:167], v[182:183]
	v_pk_fma_f32 v[30:31], v[30:31], v[168:169], v[184:185]
	v_pk_fma_f32 v[32:33], v[32:33], v[170:171], v[186:187]
	v_mul_f32_e32 v172, v31, v31
	v_mul_f32_e32 v173, v33, v33
	v_fmac_f32_e32 v172, v30, v30
	v_fmac_f32_e32 v173, v32, v32
	v_add_f32_e32 v172, v172, v173
	v_mul_f32_e32 v173, v27, v27
	v_mul_f32_e32 v174, v29, v29
	v_fmac_f32_e32 v173, v26, v26
	v_fmac_f32_e32 v174, v28, v28
	v_add_f32_e32 v173, v173, v174
	v_add_f32_e32 v172, v172, v173
	v_mul_f32_e32 v173, v23, v23
	v_mul_f32_e32 v174, v25, v25
	v_fmac_f32_e32 v173, v22, v22
	v_fmac_f32_e32 v174, v24, v24
	v_add_f32_e32 v173, v173, v174
	v_mul_f32_e32 v174, v19, v19
	v_mul_f32_e32 v175, v21, v21
	v_fmac_f32_e32 v174, v18, v18
	v_fmac_f32_e32 v175, v20, v20
	v_add_f32_e32 v174, v174, v175
	v_add_f32_e32 v173, v173, v174
	v_add_f32_e32 v244, v172, v173
	s_add_i32 s5, s5, -1
	s_cmp_eq_u32 s5, 0
	s_cbranch_scc1 .Lf9a_done
; __device__ __forceinline__ u32x4 pack8(const f32x4 a, const f32x4 b) { u32x4 w; w.x = cvt_pk_bf16(a[0], a[1]); w.y = cvt_pk_bf16(a[2], a[3]); w.z = cvt_pk_bf16(b[0], b[1]); w.w = cvt_pk_bf16(b[2], b[3]); return w; }
;     __device__ __forceinline__ void operator()(const f32x4 (&acc)[2][2][4][2], const Unit& u, int wr, int wc, int fr, int fq) const {
;     ...
;         for (int r = 0; r < 8; ++r) { const int ai = r >> 2, m = r & 3; const int row = EPI_ROW; float sq = 0.f;
;             if (r < 7) RES_LOAD(n16, n32, r + 1);
;             u32x4 pn_[2], ps_[2];
; #pragma unroll
;             for (int bj = 0; bj < 2; ++bj) {
;                 f32x4 o0, o1;
;                 if (XOLD16) unpack8(c16[bj], o0, o1); else { o0 = c32[bj][0]; o1 = c32[bj][1]; }
;                 const f32x4 v0 = o0 + gv[bj][0] * acc[ai][bj][m][0], v1 = o1 + gv[bj][1] * acc[ai][bj][m][1];
;                 pn_[bj] = pack8(v0, v1);
;                 sq += ((v0[0] * v0[0] + v0[1] * v0[1]) + (v0[2] * v0[2] + v0[3] * v0[3])) + ((v1[0] * v1[0] + v1[1] * v1[1]) + (v1[2] * v1[2] + v1[3] * v1[3]));
;                 if (XS) ps_[bj] = pack8(v0 * cs[bj][0], v1 * cs[bj][1]); }
;             { const size_t seg = (size_t)(row - fr) * DM + u.pn * BM + wc * 64;
;               store_lines(st, pn_[0], pn_[1], fr, fq, xnew + seg, DM);
;               if (XS) store_lines(st, ps_[0], ps_[1], fr, fq, xs + seg, DM); }
;             sq += __shfl_xor(sq, 16); sq += __shfl_xor(sq, 32);
;             if (fq == 0) ssq[(size_t)row * 16 + u.pn * 4 + wc] = sq;
.Lf9a_rg7:
	s_waitcnt vmcnt(0)
	v_lshlrev_b32_e32 v184, 16, v130
	v_and_b32_e32 v185, 0xffff0000, v130
	v_lshlrev_b32_e32 v186, 16, v131
	v_and_b32_e32 v187, 0xffff0000, v131
	v_lshlrev_b32_e32 v180, 16, v132
	v_and_b32_e32 v181, 0xffff0000, v132
	v_lshlrev_b32_e32 v182, 16, v133
	v_and_b32_e32 v183, 0xffff0000, v133
	v_lshlrev_b32_e32 v176, 16, v134
	v_and_b32_e32 v177, 0xffff0000, v134
	v_lshlrev_b32_e32 v178, 16, v135
	v_and_b32_e32 v179, 0xffff0000, v135
	v_lshlrev_b32_e32 v172, 16, v136
	v_and_b32_e32 v173, 0xffff0000, v136
	v_lshlrev_b32_e32 v174, 16, v137
	v_and_b32_e32 v175, 0xffff0000, v137
	v_pk_fma_f32 v[2:3], v[2:3], v[156:157], v[172:173]
	v_pk_fma_f32 v[4:5], v[4:5], v[158:159], v[174:175]
	v_pk_fma_f32 v[6:7], v[6:7], v[160:161], v[176:177]
	v_pk_fma_f32 v[8:9], v[8:9], v[162:163], v[178:179]
	v_pk_fma_f32 v[10:11], v[10:11], v[164:165], v[180:181]
	v_pk_fma_f32 v[12:13], v[12:13], v[166:167], v[182:183]
	v_pk_fma_f32 v[14:15], v[14:15], v[168:169], v[184:185]
	v_pk_fma_f32 v[16:17], v[16:17], v[170:171], v[186:187]
	v_mul_f32_e32 v172, v15, v15
	v_mul_f32_e32 v173, v17, v17
	v_fmac_f32_e32 v172, v14, v14
	v_fmac_f32_e32 v173, v16, v16
	v_add_f32_e32 v172, v172, v173
	v_mul_f32_e32 v173, v11, v11
	v_mul_f32_e32 v174, v13, v13
	v_fmac_f32_e32 v173, v10, v10
	v_fmac_f32_e32 v174, v12, v12
	v_add_f32_e32 v173, v173, v174
	v_add_f32_e32 v172, v172, v173
	v_mul_f32_e32 v173, v7, v7
	v_mul_f32_e32 v174, v9, v9
	v_fmac_f32_e32 v173, v6, v6
	v_fmac_f32_e32 v174, v8, v8
	v_add_f32_e32 v173, v173, v174
	v_mul_f32_e32 v174, v3, v3
	v_mul_f32_e32 v175, v5, v5
	v_fmac_f32_e32 v174, v2, v2
	v_fmac_f32_e32 v175, v4, v4
	v_add_f32_e32 v174, v174, v175
	v_add_f32_e32 v173, v173, v174
	v_add_f32_e32 v130, v172, v173
	s_add_i32 s5, s5, -1
	s_cmp_eq_u32 s5, 0
	s_cbranch_scc1 .Lf9a_done
	s_branch .Lf9a_rg0
.Lf9a_done:
	ds_bpermute_b32 v197, v255, v196
	ds_bpermute_b32 v205, v255, v204
	ds_bpermute_b32 v213, v255, v212
	ds_bpermute_b32 v221, v255, v220
	ds_bpermute_b32 v229, v255, v228
	ds_bpermute_b32 v237, v255, v236
	ds_bpermute_b32 v245, v255, v244
	ds_bpermute_b32 v131, v255, v130
	s_waitcnt lgkmcnt(0)
	v_add_f32_e32 v196, v196, v197
	v_add_f32_e32 v204, v204, v205
	v_add_f32_e32 v212, v212, v213
	v_add_f32_e32 v220, v220, v221
	v_add_f32_e32 v228, v228, v229
	v_add_f32_e32 v236, v236, v237
	v_add_f32_e32 v244, v244, v245
	v_add_f32_e32 v130, v130, v131
	ds_bpermute_b32 v197, v252, v196
	ds_bpermute_b32 v205, v252, v204
	ds_bpermute_b32 v213, v252, v212
	ds_bpermute_b32 v221, v252, v220
	ds_bpermute_b32 v229, v252, v228
	ds_bpermute_b32 v237, v252, v236
	ds_bpermute_b32 v245, v252, v244
	ds_bpermute_b32 v131, v252, v130
	s_waitcnt lgkmcnt(0)
	v_add_f32_e32 v196, v196, v197
	v_add_f32_e32 v204, v204, v205
	v_add_f32_e32 v212, v212, v213
	v_add_f32_e32 v220, v220, v221
	v_add_f32_e32 v228, v228, v229
	v_add_f32_e32 v236, v236, v237
	v_add_f32_e32 v244, v244, v245
	v_add_f32_e32 v130, v130, v131
	s_lshl_b32 s4, s1, 6
	s_lshl_b32 s5, s10, 4
	s_add_u32 s4, s4, s5
	s_lshl_b32 s5, s53, 2
	s_add_u32 s4, s4, s5
	s_add_u32 s38, s16, s4
	s_addc_u32 s39, s17, 0
	s_add_u32 s36, s38, 0x2000
	s_addc_u32 s37, s39, 0
	s_mov_b64 exec, 0xffff
	global_store_dword v146, v196, s[38:39] offset:0 sc0 sc1
	global_store_dword v146, v204, s[38:39] offset:1024 sc0 sc1
	global_store_dword v146, v212, s[38:39] offset:2048 sc0 sc1
	global_store_dword v146, v220, s[38:39] offset:3072 sc0 sc1
	global_store_dword v146, v228, s[36:37] offset:0 sc0 sc1
	global_store_dword v146, v236, s[36:37] offset:1024 sc0 sc1
	global_store_dword v146, v244, s[36:37] offset:2048 sc0 sc1
	global_store_dword v146, v130, s[36:37] offset:3072 sc0 sc1
	s_mov_b64 exec, -1
	s_waitcnt vmcnt(0)
	s_barrier
	v_cmp_eq_u32_e32 vcc, 0, v0
	s_and_saveexec_b64 s[30:31], vcc
	s_cbranch_execz .Lf9_sync_done
	s_lshl_b32 s4, s98, 2
	s_add_u32 s4, s4, 0x83800
	s_add_u32 s4, s78, s4
	s_addc_u32 s5, s79, 0
	v_mov_b32_e32 v253, 0
	v_mov_b32_e32 v172, 1
	global_atomic_add v253, v172, s[4:5]
	s_mov_b32 s6, 0

; __device__ __forceinline__ float rstd_from(const float* ssq, int row) {
;     const f32x4* p = (const f32x4*)(ssq + (size_t)row * 16);
;     const f32x4 s = (p[0] + p[1]) + (p[2] + p[3]);
;     return __builtin_amdgcn_rsqf(((s[0] + s[1]) + (s[2] + s[3])) * (1.0f / DM) + RMS_EPS);
; }
; __device__ __forceinline__ void p10_final(const Args& A, int lane, int wave, float* outp) {
;     const float* ssq = (const float*)(A.ws + WS_SSQF); const bf16_t* X3 = (const bf16_t*)(A.ws + WS_X3);
;     const int gw = blockIdx.x * 8 + wave, NGW = gridDim.x * 8;
;     for (int m = gw; m < M; m += NGW) { const float rs = pg8::rstd_from(ssq, m);
; #pragma unroll
;         for (int j = 0; j < 2; ++j) { const int c = 8 * lane + 512 * j; f32x4 a, b; pg8::unpack8(*(const u32x4*)(X3 + (size_t)m * DM + c), a, b);
;             *(f32x4*)(outp + (size_t)m * DM + c) = (a * rs) * *(const f32x4*)(A.g_final + c); *(f32x4*)(outp + (size_t)m * DM + c + 4) = (b * rs) * *(const f32x4*)(A.g_final + c + 4); } }
; }
.Lf9_sync_done:
	s_or_b64 exec, exec, s[30:31]
	s_barrier
	s_waitcnt lgkmcnt(0)
	s_lshl_b32 s4, s0, 2
	s_add_u32 s4, s100, s4
	s_addc_u32 s5, s101, 0
	global_load_dwordx4 v[168:171], v188, s[4:5]
	global_load_dwordx4 v[164:167], v188, s[4:5] offset:16
	global_load_dwordx4 v[160:163], v188, s[4:5] offset:128
	global_load_dwordx4 v[156:159], v188, s[4:5] offset:144
	s_lshl_b32 s4, s1, 6
	s_add_u32 s38, s16, s4
	s_addc_u32 s39, s17, 0
	s_add_u32 s36, s38, 0x2000
	s_addc_u32 s37, s39, 0
	v_mov_b32_e32 v189, 0x358637bd
	v_lshl_add_u32 v228, v190, 10, v146
	global_load_dwordx4 v[196:199], v228, s[38:39] sc0 sc1
	global_load_dwordx4 v[200:203], v228, s[38:39] offset:16 sc0 sc1
	global_load_dwordx4 v[204:207], v228, s[38:39] offset:32 sc0 sc1
	global_load_dwordx4 v[208:211], v228, s[38:39] offset:48 sc0 sc1
	global_load_dwordx4 v[212:215], v228, s[36:37] sc0 sc1
	global_load_dwordx4 v[216:219], v228, s[36:37] offset:16 sc0 sc1
	global_load_dwordx4 v[240:243], v228, s[36:37] offset:32 sc0 sc1
	global_load_dwordx4 v[244:247], v228, s[36:37] offset:48 sc0 sc1
	v_lshlrev_b32_e32 v229, 2, v1
	v_add_u32_e32 v230, 0x40, v229
	v_add_u32_e32 v231, 0x80, v229
	v_add_u32_e32 v232, 0xc0, v229
	s_waitcnt vmcnt(4)
	v_pk_add_f32 v[198:199], v[198:199], v[202:203]
	v_pk_add_f32 v[196:197], v[196:197], v[200:201]
	v_pk_add_f32 v[200:201], v[206:207], v[210:211]
	v_pk_add_f32 v[202:203], v[204:205], v[208:209]
	v_pk_add_f32 v[198:199], v[198:199], v[200:201]
	v_pk_add_f32 v[196:197], v[196:197], v[202:203]
	v_add_f32_e32 v196, v196, v197
	v_add_f32_e32 v198, v198, v199
	v_add_f32_e32 v196, v196, v198
	v_fmamk_f32 v196, v196, 0x3a800000, v189
	v_rsq_f32_e32 v196, v196
	s_waitcnt vmcnt(0)
	v_pk_add_f32 v[214:215], v[214:215], v[218:219]
	v_pk_add_f32 v[212:213], v[212:213], v[216:217]
	v_pk_add_f32 v[216:217], v[242:243], v[246:247]
	v_pk_add_f32 v[218:219], v[240:241], v[244:245]
	v_pk_add_f32 v[214:215], v[214:215], v[216:217]
	v_pk_add_f32 v[212:213], v[212:213], v[218:219]
	v_add_f32_e32 v212, v212, v213
	v_add_f32_e32 v214, v214, v215
	v_add_f32_e32 v212, v212, v214
	v_fmamk_f32 v212, v212, 0x3a800000, v189
	v_rsq_f32_e32 v212, v212
	s_nop 0
	ds_bpermute_b32 v172, v229, v196
	ds_bpermute_b32 v173, v230, v196
	ds_bpermute_b32 v174, v231, v196
	ds_bpermute_b32 v175, v232, v196
	ds_bpermute_b32 v176, v229, v212
	ds_bpermute_b32 v177, v230, v212
	ds_bpermute_b32 v178, v231, v212
	ds_bpermute_b32 v179, v232, v212
	s_waitcnt lgkmcnt(0)
	s_lshl_b32 s4, s54, 7
	s_lshl_b32 s5, s53, 11
	s_add_i32 s4, s4, s5
	s_add_i32 s4, s4, 0x20000
	v_lshlrev_b32_e32 v228, 7, v1
	v_lshl_add_u32 v228, v190, 5, v228
	v_add_u32_e32 v228, s4, v228
	v_lshl_add_u32 v229, v195, 4, s4
	v_lshrrev_b32_e32 v230, 3, v195
	v_lshlrev_b32_e32 v230, 12, v230
	v_and_b32_e32 v231, 7, v195
	v_lshl_add_u32 v230, v231, 4, v230
	v_add_u32_e32 v231, 0x8000, v230
	s_lshl_b32 s4, s1, 12
	s_lshl_b32 s5, s0, 2
	s_add_u32 s4, s4, s5
	s_add_u32 s34, s76, s4
	s_addc_u32 s35, s77, 0
	s_lshr_b32 s4, s54, 4
	s_add_u32 s4, s4, s53
	s_mov_b32 s5, 8
	s_cmp_eq_u32 s4, 1
	s_cbranch_scc1 .Lf9d_rg1
	s_cmp_eq_u32 s4, 2
	s_cbranch_scc1 .Lf9d_rg2
	s_cmp_eq_u32 s4, 3
	s_cbranch_scc1 .Lf9d_rg3
	s_cmp_eq_u32 s4, 4
	s_cbranch_scc1 .Lf9d_rg4
	s_cmp_eq_u32 s4, 5
	s_cbranch_scc1 .Lf9d_rg5
	s_cmp_eq_u32 s4, 6
	s_cbranch_scc1 .Lf9d_rg6
	s_cmp_eq_u32 s4, 7
	s_cbranch_scc1 .Lf9d_rg7
.Lf9d_rg0:
	s_add_u32 s6, s34, 0x0
	s_addc_u32 s7, s35, 0
	v_mul_f32_e32 v196, v172, v114
	v_mul_f32_e32 v197, v172, v115
	v_mul_f32_e32 v198, v172, v116
	v_mul_f32_e32 v199, v172, v117
	v_mul_f32_e32 v200, v172, v118
	v_mul_f32_e32 v201, v172, v119
	v_mul_f32_e32 v202, v172, v120
	v_mul_f32_e32 v203, v172, v121
	v_mul_f32_e32 v204, v172, v122
	v_mul_f32_e32 v205, v172, v123
	v_mul_f32_e32 v206, v172, v124
	v_mul_f32_e32 v207, v172, v125
	v_mul_f32_e32 v208, v172, v126
	v_mul_f32_e32 v209, v172, v127
	v_mul_f32_e32 v210, v172, v128
	v_mul_f32_e32 v211, v172, v129
	v_pk_mul_f32 v[196:197], v[156:157], v[196:197]
	v_pk_mul_f32 v[198:199], v[158:159], v[198:199]
	v_pk_mul_f32 v[200:201], v[160:161], v[200:201]
	v_pk_mul_f32 v[202:203], v[162:163], v[202:203]
	v_pk_mul_f32 v[204:205], v[164:165], v[204:205]
	v_pk_mul_f32 v[206:207], v[166:167], v[206:207]
	v_pk_mul_f32 v[208:209], v[168:169], v[208:209]
	v_pk_mul_f32 v[210:211], v[170:171], v[210:211]
	ds_write_b128 v228, v[208:211]
	ds_write_b128 v228, v[204:207] offset:16
	ds_read_b128 v[232:235], v229
	ds_read_b128 v[236:239], v229 offset:1024
	s_waitcnt lgkmcnt(1)
	global_store_dwordx4 v230, v[232:235], s[6:7]
	s_waitcnt lgkmcnt(0)
	global_store_dwordx4 v231, v[236:239], s[6:7]
	ds_write_b128 v228, v[200:203]
	ds_write_b128 v228, v[196:199] offset:16
	ds_read_b128 v[240:243], v229
	ds_read_b128 v[244:247], v229 offset:1024
	s_waitcnt lgkmcnt(1)
	global_store_dwordx4 v230, v[240:243], s[6:7] offset:128
	s_waitcnt lgkmcnt(0)
	global_store_dwordx4 v231, v[244:247], s[6:7] offset:128
	s_add_i32 s5, s5, -1
	s_cmp_eq_u32 s5, 0
	s_cbranch_scc1 .Lf9d_done
; __device__ __forceinline__ void p10_final(const Args& A, int lane, int wave, float* outp) {
;     const float* ssq = (const float*)(A.ws + WS_SSQF); const bf16_t* X3 = (const bf16_t*)(A.ws + WS_X3);
;     const int gw = blockIdx.x * 8 + wave, NGW = gridDim.x * 8;
;     for (int m = gw; m < M; m += NGW) { const float rs = pg8::rstd_from(ssq, m);
; #pragma unroll
;         for (int j = 0; j < 2; ++j) { const int c = 8 * lane + 512 * j; f32x4 a, b; pg8::unpack8(*(const u32x4*)(X3 + (size_t)m * DM + c), a, b);
;             *(f32x4*)(outp + (size_t)m * DM + c) = (a * rs) * *(const f32x4*)(A.g_final + c); *(f32x4*)(outp + (size_t)m * DM + c + 4) = (b * rs) * *(const f32x4*)(A.g_final + c + 4); } }
; }
.Lf9d_rg1:
	s_add_u32 s6, s34, 0x10000
	s_addc_u32 s7, s35, 0
	v_mul_f32_e32 v212, v173, v98
	v_mul_f32_e32 v213, v173, v99
	v_mul_f32_e32 v214, v173, v100
	v_mul_f32_e32 v215, v173, v101
	v_mul_f32_e32 v216, v173, v102
	v_mul_f32_e32 v217, v173, v103
	v_mul_f32_e32 v218, v173, v104
	v_mul_f32_e32 v219, v173, v105
	v_mul_f32_e32 v220, v173, v106
	v_mul_f32_e32 v221, v173, v107
	v_mul_f32_e32 v222, v173, v108
	v_mul_f32_e32 v223, v173, v109
	v_mul_f32_e32 v224, v173, v110
	v_mul_f32_e32 v225, v173, v111
	v_mul_f32_e32 v226, v173, v112
	v_mul_f32_e32 v227, v173, v113
	v_pk_mul_f32 v[212:213], v[156:157], v[212:213]
	v_pk_mul_f32 v[214:215], v[158:159], v[214:215]
	v_pk_mul_f32 v[216:217], v[160:161], v[216:217]
	v_pk_mul_f32 v[218:219], v[162:163], v[218:219]
	v_pk_mul_f32 v[220:221], v[164:165], v[220:221]
	v_pk_mul_f32 v[222:223], v[166:167], v[222:223]
	v_pk_mul_f32 v[224:225], v[168:169], v[224:225]
	v_pk_mul_f32 v[226:227], v[170:171], v[226:227]
	ds_write_b128 v228, v[224:227]
	ds_write_b128 v228, v[220:223] offset:16
	ds_read_b128 v[240:243], v229
	ds_read_b128 v[244:247], v229 offset:1024
	s_waitcnt lgkmcnt(1)
	global_store_dwordx4 v230, v[240:243], s[6:7]
	s_waitcnt lgkmcnt(0)
	global_store_dwordx4 v231, v[244:247], s[6:7]
	ds_write_b128 v228, v[216:219]
	ds_write_b128 v228, v[212:215] offset:16
	ds_read_b128 v[240:243], v229
	ds_read_b128 v[244:247], v229 offset:1024
	s_waitcnt lgkmcnt(1)
	global_store_dwordx4 v230, v[240:243], s[6:7] offset:128
	s_waitcnt lgkmcnt(0)
	global_store_dwordx4 v231, v[244:247], s[6:7] offset:128
	s_add_i32 s5, s5, -1
	s_cmp_eq_u32 s5, 0
	s_cbranch_scc1 .Lf9d_done
.Lf9d_rg2:
	s_add_u32 s6, s34, 0x20000
	s_addc_u32 s7, s35, 0
	v_mul_f32_e32 v196, v174, v82
	v_mul_f32_e32 v197, v174, v83
	v_mul_f32_e32 v198, v174, v84
	v_mul_f32_e32 v199, v174, v85
	v_mul_f32_e32 v200, v174, v86
	v_mul_f32_e32 v201, v174, v87
	v_mul_f32_e32 v202, v174, v88
	v_mul_f32_e32 v203, v174, v89
	v_mul_f32_e32 v204, v174, v90
	v_mul_f32_e32 v205, v174, v91
	v_mul_f32_e32 v206, v174, v92
	v_mul_f32_e32 v207, v174, v93
	v_mul_f32_e32 v208, v174, v94
	v_mul_f32_e32 v209, v174, v95
	v_mul_f32_e32 v210, v174, v96
	v_mul_f32_e32 v211, v174, v97
	v_pk_mul_f32 v[196:197], v[156:157], v[196:197]
	v_pk_mul_f32 v[198:199], v[158:159], v[198:199]
	v_pk_mul_f32 v[200:201], v[160:161], v[200:201]
	v_pk_mul_f32 v[202:203], v[162:163], v[202:203]
	v_pk_mul_f32 v[204:205], v[164:165], v[204:205]
	v_pk_mul_f32 v[206:207], v[166:167], v[206:207]
	v_pk_mul_f32 v[208:209], v[168:169], v[208:209]
	v_pk_mul_f32 v[210:211], v[170:171], v[210:211]
	ds_write_b128 v228, v[208:211]
	ds_write_b128 v228, v[204:207] offset:16
	ds_read_b128 v[232:235], v229
	ds_read_b128 v[236:239], v229 offset:1024
	s_waitcnt lgkmcnt(1)
	global_store_dwordx4 v230, v[232:235], s[6:7]
	s_waitcnt lgkmcnt(0)
	global_store_dwordx4 v231, v[236:239], s[6:7]
	ds_write_b128 v228, v[200:203]
	ds_write_b128 v228, v[196:199] offset:16
	ds_read_b128 v[240:243], v229
	ds_read_b128 v[244:247], v229 offset:1024
	s_waitcnt lgkmcnt(1)
	global_store_dwordx4 v230, v[240:243], s[6:7] offset:128
	s_waitcnt lgkmcnt(0)
	global_store_dwordx4 v231, v[244:247], s[6:7] offset:128
	s_add_i32 s5, s5, -1
	s_cmp_eq_u32 s5, 0
	s_cbranch_scc1 .Lf9d_done
.Lf9d_rg3:
	s_add_u32 s6, s34, 0x30000
	s_addc_u32 s7, s35, 0
	v_mul_f32_e32 v212, v175, v66
	v_mul_f32_e32 v213, v175, v67
	v_mul_f32_e32 v214, v175, v68
	v_mul_f32_e32 v215, v175, v69
	v_mul_f32_e32 v216, v175, v70
	v_mul_f32_e32 v217, v175, v71
	v_mul_f32_e32 v218, v175, v72
	v_mul_f32_e32 v219, v175, v73
	v_mul_f32_e32 v220, v175, v74
	v_mul_f32_e32 v221, v175, v75
	v_mul_f32_e32 v222, v175, v76
	v_mul_f32_e32 v223, v175, v77
	v_mul_f32_e32 v224, v175, v78
	v_mul_f32_e32 v225, v175, v79
	v_mul_f32_e32 v226, v175, v80
	v_mul_f32_e32 v227, v175, v81
	v_pk_mul_f32 v[212:213], v[156:157], v[212:213]
	v_pk_mul_f32 v[214:215], v[158:159], v[214:215]
	v_pk_mul_f32 v[216:217], v[160:161], v[216:217]
	v_pk_mul_f32 v[218:219], v[162:163], v[218:219]
	v_pk_mul_f32 v[220:221], v[164:165], v[220:221]
	v_pk_mul_f32 v[222:223], v[166:167], v[222:223]
	v_pk_mul_f32 v[224:225], v[168:169], v[224:225]
	v_pk_mul_f32 v[226:227], v[170:171], v[226:227]
	ds_write_b128 v228, v[224:227]
	ds_write_b128 v228, v[220:223] offset:16
	ds_read_b128 v[240:243], v229
	ds_read_b128 v[244:247], v229 offset:1024
	s_waitcnt lgkmcnt(1)
	global_store_dwordx4 v230, v[240:243], s[6:7]
	s_waitcnt lgkmcnt(0)
	global_store_dwordx4 v231, v[244:247], s[6:7]
	ds_write_b128 v228, v[216:219]
	ds_write_b128 v228, v[212:215] offset:16
	ds_read_b128 v[240:243], v229
	ds_read_b128 v[244:247], v229 offset:1024
	s_waitcnt lgkmcnt(1)
	global_store_dwordx4 v230, v[240:243], s[6:7] offset:128
	s_waitcnt lgkmcnt(0)
	global_store_dwordx4 v231, v[244:247], s[6:7] offset:128
	s_add_i32 s5, s5, -1
	s_cmp_eq_u32 s5, 0
	s_cbranch_scc1 .Lf9d_done
; __device__ __forceinline__ void p10_final(const Args& A, int lane, int wave, float* outp) {
;     const float* ssq = (const float*)(A.ws + WS_SSQF); const bf16_t* X3 = (const bf16_t*)(A.ws + WS_X3);
;     const int gw = blockIdx.x * 8 + wave, NGW = gridDim.x * 8;
;     for (int m = gw; m < M; m += NGW) { const float rs = pg8::rstd_from(ssq, m);
; #pragma unroll
;         for (int j = 0; j < 2; ++j) { const int c = 8 * lane + 512 * j; f32x4 a, b; pg8::unpack8(*(const u32x4*)(X3 + (size_t)m * DM + c), a, b);
;             *(f32x4*)(outp + (size_t)m * DM + c) = (a * rs) * *(const f32x4*)(A.g_final + c); *(f32x4*)(outp + (size_t)m * DM + c + 4) = (b * rs) * *(const f32x4*)(A.g_final + c + 4); } }
; }
.Lf9d_rg4:
	s_add_u32 s6, s34, 0x80000
	s_addc_u32 s7, s35, 0
	v_mul_f32_e32 v196, v176, v50
	v_mul_f32_e32 v197, v176, v51
	v_mul_f32_e32 v198, v176, v52
	v_mul_f32_e32 v199, v176, v53
	v_mul_f32_e32 v200, v176, v54
	v_mul_f32_e32 v201, v176, v55
	v_mul_f32_e32 v202, v176, v56
	v_mul_f32_e32 v203, v176, v57
	v_mul_f32_e32 v204, v176, v58
	v_mul_f32_e32 v205, v176, v59
	v_mul_f32_e32 v206, v176, v60
	v_mul_f32_e32 v207, v176, v61
	v_mul_f32_e32 v208, v176, v62
	v_mul_f32_e32 v209, v176, v63
	v_mul_f32_e32 v210, v176, v64
	v_mul_f32_e32 v211, v176, v65
	v_pk_mul_f32 v[196:197], v[156:157], v[196:197]
	v_pk_mul_f32 v[198:199], v[158:159], v[198:199]
	v_pk_mul_f32 v[200:201], v[160:161], v[200:201]
	v_pk_mul_f32 v[202:203], v[162:163], v[202:203]
	v_pk_mul_f32 v[204:205], v[164:165], v[204:205]
	v_pk_mul_f32 v[206:207], v[166:167], v[206:207]
	v_pk_mul_f32 v[208:209], v[168:169], v[208:209]
	v_pk_mul_f32 v[210:211], v[170:171], v[210:211]
	ds_write_b128 v228, v[208:211]
	ds_write_b128 v228, v[204:207] offset:16
	ds_read_b128 v[232:235], v229
	ds_read_b128 v[236:239], v229 offset:1024
	s_waitcnt lgkmcnt(1)
	global_store_dwordx4 v230, v[232:235], s[6:7]
	s_waitcnt lgkmcnt(0)
	global_store_dwordx4 v231, v[236:239], s[6:7]
	ds_write_b128 v228, v[200:203]
	ds_write_b128 v228, v[196:199] offset:16
	ds_read_b128 v[240:243], v229
	ds_read_b128 v[244:247], v229 offset:1024
	s_waitcnt lgkmcnt(1)
	global_store_dwordx4 v230, v[240:243], s[6:7] offset:128
	s_waitcnt lgkmcnt(0)
	global_store_dwordx4 v231, v[244:247], s[6:7] offset:128
	s_add_i32 s5, s5, -1
	s_cmp_eq_u32 s5, 0
	s_cbranch_scc1 .Lf9d_done
.Lf9d_rg5:
	s_add_u32 s6, s34, 0x90000
	s_addc_u32 s7, s35, 0
	v_mul_f32_e32 v212, v177, v34
	v_mul_f32_e32 v213, v177, v35
	v_mul_f32_e32 v214, v177, v36
	v_mul_f32_e32 v215, v177, v37
	v_mul_f32_e32 v216, v177, v38
	v_mul_f32_e32 v217, v177, v39
	v_mul_f32_e32 v218, v177, v40
	v_mul_f32_e32 v219, v177, v41
	v_mul_f32_e32 v220, v177, v42
	v_mul_f32_e32 v221, v177, v43
	v_mul_f32_e32 v222, v177, v44
	v_mul_f32_e32 v223, v177, v45
	v_mul_f32_e32 v224, v177, v46
	v_mul_f32_e32 v225, v177, v47
	v_mul_f32_e32 v226, v177, v48
	v_mul_f32_e32 v227, v177, v49
	v_pk_mul_f32 v[212:213], v[156:157], v[212:213]
	v_pk_mul_f32 v[214:215], v[158:159], v[214:215]
	v_pk_mul_f32 v[216:217], v[160:161], v[216:217]
	v_pk_mul_f32 v[218:219], v[162:163], v[218:219]
	v_pk_mul_f32 v[220:221], v[164:165], v[220:221]
	v_pk_mul_f32 v[222:223], v[166:167], v[222:223]
	v_pk_mul_f32 v[224:225], v[168:169], v[224:225]
	v_pk_mul_f32 v[226:227], v[170:171], v[226:227]
	ds_write_b128 v228, v[224:227]
	ds_write_b128 v228, v[220:223] offset:16
	ds_read_b128 v[240:243], v229
	ds_read_b128 v[244:247], v229 offset:1024
	s_waitcnt lgkmcnt(1)
	global_store_dwordx4 v230, v[240:243], s[6:7]
	s_waitcnt lgkmcnt(0)
	global_store_dwordx4 v231, v[244:247], s[6:7]
	ds_write_b128 v228, v[216:219]
	ds_write_b128 v228, v[212:215] offset:16
	ds_read_b128 v[240:243], v229
	ds_read_b128 v[244:247], v229 offset:1024
	s_waitcnt lgkmcnt(1)
	global_store_dwordx4 v230, v[240:243], s[6:7] offset:128
	s_waitcnt lgkmcnt(0)
	global_store_dwordx4 v231, v[244:247], s[6:7] offset:128
	s_add_i32 s5, s5, -1
	s_cmp_eq_u32 s5, 0
	s_cbranch_scc1 .Lf9d_done
.Lf9d_rg6:
	s_add_u32 s6, s34, 0xa0000
	s_addc_u32 s7, s35, 0
	v_mul_f32_e32 v196, v178, v18
	v_mul_f32_e32 v197, v178, v19
	v_mul_f32_e32 v198, v178, v20
	v_mul_f32_e32 v199, v178, v21
	v_mul_f32_e32 v200, v178, v22
	v_mul_f32_e32 v201, v178, v23
	v_mul_f32_e32 v202, v178, v24
	v_mul_f32_e32 v203, v178, v25
	v_mul_f32_e32 v204, v178, v26
	v_mul_f32_e32 v205, v178, v27
	v_mul_f32_e32 v206, v178, v28
	v_mul_f32_e32 v207, v178, v29
	v_mul_f32_e32 v208, v178, v30
	v_mul_f32_e32 v209, v178, v31
	v_mul_f32_e32 v210, v178, v32
	v_mul_f32_e32 v211, v178, v33
	v_pk_mul_f32 v[196:197], v[156:157], v[196:197]
	v_pk_mul_f32 v[198:199], v[158:159], v[198:199]
	v_pk_mul_f32 v[200:201], v[160:161], v[200:201]
	v_pk_mul_f32 v[202:203], v[162:163], v[202:203]
	v_pk_mul_f32 v[204:205], v[164:165], v[204:205]
	v_pk_mul_f32 v[206:207], v[166:167], v[206:207]
	v_pk_mul_f32 v[208:209], v[168:169], v[208:209]
	v_pk_mul_f32 v[210:211], v[170:171], v[210:211]
	ds_write_b128 v228, v[208:211]
	ds_write_b128 v228, v[204:207] offset:16
	ds_read_b128 v[232:235], v229
	ds_read_b128 v[236:239], v229 offset:1024
	s_waitcnt lgkmcnt(1)
	global_store_dwordx4 v230, v[232:235], s[6:7]
	s_waitcnt lgkmcnt(0)
	global_store_dwordx4 v231, v[236:239], s[6:7]
	ds_write_b128 v228, v[200:203]
	ds_write_b128 v228, v[196:199] offset:16
	ds_read_b128 v[240:243], v229
	ds_read_b128 v[244:247], v229 offset:1024
	s_waitcnt lgkmcnt(1)
	global_store_dwordx4 v230, v[240:243], s[6:7] offset:128
	s_waitcnt lgkmcnt(0)
	global_store_dwordx4 v231, v[244:247], s[6:7] offset:128
	s_add_i32 s5, s5, -1
	s_cmp_eq_u32 s5, 0
	s_cbranch_scc1 .Lf9d_done
.Lf9d_rg7:
	s_add_u32 s6, s34, 0xb0000
	s_addc_u32 s7, s35, 0
	v_mul_f32_e32 v212, v179, v2
	v_mul_f32_e32 v213, v179, v3
	v_mul_f32_e32 v214, v179, v4
	v_mul_f32_e32 v215, v179, v5
	v_mul_f32_e32 v216, v179, v6
	v_mul_f32_e32 v217, v179, v7
	v_mul_f32_e32 v218, v179, v8
	v_mul_f32_e32 v219, v179, v9
	v_mul_f32_e32 v220, v179, v10
	v_mul_f32_e32 v221, v179, v11
	v_mul_f32_e32 v222, v179, v12
	v_mul_f32_e32 v223, v179, v13
	v_mul_f32_e32 v224, v179, v14
	v_mul_f32_e32 v225, v179, v15
	v_mul_f32_e32 v226, v179, v16
	v_mul_f32_e32 v227, v179, v17
	v_pk_mul_f32 v[212:213], v[156:157], v[212:213]
	v_pk_mul_f32 v[214:215], v[158:159], v[214:215]
	v_pk_mul_f32 v[216:217], v[160:161], v[216:217]
	v_pk_mul_f32 v[218:219], v[162:163], v[218:219]
	v_pk_mul_f32 v[220:221], v[164:165], v[220:221]
	v_pk_mul_f32 v[222:223], v[166:167], v[222:223]
	v_pk_mul_f32 v[224:225], v[168:169], v[224:225]
	v_pk_mul_f32 v[226:227], v[170:171], v[226:227]
	ds_write_b128 v228, v[224:227]
	ds_write_b128 v228, v[220:223] offset:16
	ds_read_b128 v[240:243], v229
	ds_read_b128 v[244:247], v229 offset:1024
	s_waitcnt lgkmcnt(1)
	global_store_dwordx4 v230, v[240:243], s[6:7]
	s_waitcnt lgkmcnt(0)
	global_store_dwordx4 v231, v[244:247], s[6:7]
	ds_write_b128 v228, v[216:219]
	ds_write_b128 v228, v[212:215] offset:16
	ds_read_b128 v[240:243], v229
	ds_read_b128 v[244:247], v229 offset:1024
	s_waitcnt lgkmcnt(1)
	global_store_dwordx4 v230, v[240:243], s[6:7] offset:128
	s_waitcnt lgkmcnt(0)
	global_store_dwordx4 v231, v[244:247], s[6:7] offset:128
	s_add_i32 s5, s5, -1
	s_cmp_eq_u32 s5, 0
	s_cbranch_scc1 .Lf9d_done
	s_branch .Lf9d_rg0
.Lf9d_done:
	s_and_b64 vcc, exec, s[2:3]
	s_mov_b64 s[0:1], -1
	s_cbranch_vccnz .LBB0_1057
	s_andn2_b64 vcc, exec, s[14:15]
	s_cbranch_vccnz .LBB0_1056
	s_barrier
	s_branch .LBB0_1056
